# GEMM main loop: LDS fragment reads issued ahead of the pointer/m0 SALU in load segments 2 and 4
# baseline (speedup 1.0000x reference)
; #define PG8_STAGE(bufoff, gbase, voff) do { _Pragma("unroll") for (int _i = 0; _i < 2; ++_i) \
;         __builtin_amdgcn_global_load_lds((const unsigned*)((const char*)(gbase) + (voff)[_i]), (LAS unsigned*)(lds + (bufoff) + ldsw + _i * 8192), 16, 0, 0); } while (0)
; #define PG8_LDA(dst, b, h) do { _Pragma("unroll") for (int m = 0; m < 4; ++m) _Pragma("unroll") for (int k = 0; k < 2; ++k) dst[m][k] = *(const LAS bf16x8*)(lds + PG8_SA(b, h) + aoff + m * 2048 + k * 1024); } while (0)
; #define PG8_LDB(dst, b, h) do { _Pragma("unroll") for (int n = 0; n < 2; ++n) _Pragma("unroll") for (int k = 0; k < 2; ++k) dst[n][k] = *(const LAS bf16x8*)(lds + PG8_SB(b, h) + boff + n * 2048 + k * 1024); } while (0)
; #define PG8_MMA(ai, bj, At, Bt) do { __builtin_amdgcn_s_setprio(1); _Pragma("unroll") for (int m = 0; m < 4; ++m) _Pragma("unroll") for (int n = 0; n < 2; ++n) _Pragma("unroll") for (int k = 0; k < 2; ++k) \
;         acc[ai][bj][m][n] = __builtin_amdgcn_mfma_f32_16x16x32_bf16(Bt[n][k], At[m][k], acc[ai][bj][m][n], 0, 0, 0); __builtin_amdgcn_s_setprio(0); } while (0)
; #define PG8_WAIT_V(n) asm volatile("s_waitcnt vmcnt(" #n ")" ::: "memory")
; #define PG8_WAIT_L(n) asm volatile("s_waitcnt lgkmcnt(" #n ")" ::: "memory")
; #define PG8_BAR __builtin_amdgcn_s_barrier()
; #define PG8_SCHED __builtin_amdgcn_sched_barrier(0)
; __device__ __forceinline__ void gemm_phase(LAS unsigned char* lds, const GemmD g, const Sched& S, const Epi& E) {
;     ...
;             const bool last = (t == nt - 2);
;             const char* a1 = cA + (size_t)(t + 1) * kstep;
;             const char* a2 = last ? nA : cA + (size_t)(t + 2) * kstep; const char* b2 = last ? nB : cB + (size_t)(t + 2) * kstep;
;             const char* a3 = a2 + kstep; const char* b3 = b2 + kstep;
;             PG8_LDB(B0, 0, 0); PG8_LDB(B1, 0, 1); PG8_SCHED; PG8_LDA(At, 0, 0); PG8_STAGE(PG8_SA(1, 1), a1 + hstepA, voffA);
;             PG8_WAIT_V(8); PG8_WAIT_L(0); PG8_BAR; PG8_MMA(0, 0, At, B0); PG8_MMA(0, 1, At, B1); PG8_BAR; PG8_SCHED;
;             PG8_LDA(At, 0, 1); PG8_STAGE(PG8_SB(0, 0), b2, voffB); PG8_STAGE(PG8_SB(0, 1), b2 + hstepB, voffB); PG8_STAGE(PG8_SA(0, 0), a2, voffA);
;             PG8_WAIT_V(8); PG8_WAIT_L(0); PG8_BAR; PG8_MMA(1, 0, At, B0); PG8_MMA(1, 1, At, B1); PG8_BAR; PG8_SCHED;
.Lprio_done:
	v_add_u32_e32 v240, 0x10000, v160
	v_add_u32_e32 v241, 0x14000, v160
	v_add_u32_e32 v242, 0x18000, v160
	v_add_u32_e32 v243, 0x1c000, v160
	ds_read_b128 v[130:133], v240
	ds_read_b128 v[146:149], v240 offset:1024
	ds_read_b128 v[150:153], v240 offset:2048
	ds_read_b128 v[154:157], v240 offset:3072
	ds_read_b128 v[162:165], v241
	ds_read_b128 v[166:169], v241 offset:1024
	ds_read_b128 v[170:173], v241 offset:2048
	ds_read_b128 v[174:177], v241 offset:3072
	s_add_i32 m0, s31, 0xc000
	ds_read_b128 v[182:185], v161
	ds_read_b128 v[186:189], v161 offset:1024
	ds_read_b128 v[190:193], v161 offset:2048
	ds_read_b128 v[216:219], v161 offset:3072
	ds_read_b128 v[220:223], v161 offset:4096
	ds_read_b128 v[224:227], v161 offset:5120
	ds_read_b128 v[228:231], v161 offset:6144
	ds_read_b128 v[236:239], v161 offset:7168
	global_load_lds_dwordx4 v142, s[8:9]
	s_add_i32 m0, s31, 0xe000
	s_nop 0
	global_load_lds_dwordx4 v144, s[8:9]
	s_add_i32 s92, s26, 2
	s_add_u32 s93, s8, 0x80
	s_addc_u32 s27, s9, 0
	s_add_i32 s22, 0, 0x10000
	s_cmp_eq_u32 s11, s26
	s_cselect_b32 s27, s1, s27
	s_cselect_b32 s26, s0, s93
	s_cselect_b32 vcc_hi, s17, s35
	s_cselect_b32 vcc_lo, s16, s34
	s_add_i32 s23, 0, 0x14000
	s_waitcnt vmcnt(8)
	s_waitcnt lgkmcnt(0)
	s_barrier
	v_mfma_f32_16x16x32_bf16 v[126:129], v[130:133], v[182:185], 0
	v_mfma_f32_16x16x32_bf16 v[122:125], v[150:153], v[182:185], 0
	v_mfma_f32_16x16x32_bf16 v[110:113], v[130:133], v[190:193], 0
	v_mfma_f32_16x16x32_bf16 v[106:109], v[150:153], v[190:193], 0
	v_mfma_f32_16x16x32_bf16 v[94:97], v[130:133], v[220:223], 0
	v_mfma_f32_16x16x32_bf16 v[90:93], v[150:153], v[220:223], 0
	v_mfma_f32_16x16x32_bf16 v[78:81], v[130:133], v[228:231], 0
	v_mfma_f32_16x16x32_bf16 v[74:77], v[150:153], v[228:231], 0
	v_mfma_f32_16x16x32_bf16 v[126:129], v[146:149], v[186:189], v[126:129]
	v_mfma_f32_16x16x32_bf16 v[122:125], v[154:157], v[186:189], v[122:125]
	v_mfma_f32_16x16x32_bf16 v[110:113], v[146:149], v[216:219], v[110:113]
	v_mfma_f32_16x16x32_bf16 v[106:109], v[154:157], v[216:219], v[106:109]
	v_mfma_f32_16x16x32_bf16 v[94:97], v[146:149], v[224:227], v[94:97]
	v_mfma_f32_16x16x32_bf16 v[90:93], v[154:157], v[224:227], v[90:93]
	v_mfma_f32_16x16x32_bf16 v[78:81], v[146:149], v[236:239], v[78:81]
	v_mfma_f32_16x16x32_bf16 v[74:77], v[154:157], v[236:239], v[74:77]
	v_mfma_f32_16x16x32_bf16 v[118:121], v[162:165], v[182:185], 0
	v_mfma_f32_16x16x32_bf16 v[114:117], v[170:173], v[182:185], 0
	v_mfma_f32_16x16x32_bf16 v[102:105], v[162:165], v[190:193], 0
	v_mfma_f32_16x16x32_bf16 v[98:101], v[170:173], v[190:193], 0
	v_mfma_f32_16x16x32_bf16 v[86:89], v[162:165], v[220:223], 0
	v_mfma_f32_16x16x32_bf16 v[82:85], v[170:173], v[220:223], 0
	v_mfma_f32_16x16x32_bf16 v[70:73], v[162:165], v[228:231], 0
	v_mfma_f32_16x16x32_bf16 v[66:69], v[170:173], v[228:231], 0
	v_mfma_f32_16x16x32_bf16 v[118:121], v[166:169], v[186:189], v[118:121]
	v_mfma_f32_16x16x32_bf16 v[114:117], v[174:177], v[186:189], v[114:117]
	v_mfma_f32_16x16x32_bf16 v[102:105], v[166:169], v[216:219], v[102:105]
	v_mfma_f32_16x16x32_bf16 v[98:101], v[174:177], v[216:219], v[98:101]
	v_mfma_f32_16x16x32_bf16 v[86:89], v[166:169], v[224:227], v[86:89]
	v_mfma_f32_16x16x32_bf16 v[82:85], v[174:177], v[224:227], v[82:85]
	v_mfma_f32_16x16x32_bf16 v[70:73], v[166:169], v[236:239], v[70:73]
	v_mfma_f32_16x16x32_bf16 v[66:69], v[174:177], v[236:239], v[66:69]
	s_barrier
	ds_read_b128 v[182:185], v161 offset:16384
	ds_read_b128 v[186:189], v161 offset:17408
	ds_read_b128 v[190:193], v161 offset:18432
	ds_read_b128 v[216:219], v161 offset:19456
	ds_read_b128 v[220:223], v161 offset:20480
	ds_read_b128 v[224:227], v161 offset:21504
	ds_read_b128 v[228:231], v161 offset:22528
	s_add_i32 s22, s22, s30
	s_mov_b32 m0, s22
	ds_read_b128 v[236:239], v161 offset:23552
	global_load_lds_dwordx4 v136, vcc
	s_add_i32 m0, s22, 0x2000
	s_add_i32 s22, s23, s30
	global_load_lds_dwordx4 v140, vcc
	s_mov_b32 m0, s22
	s_nop 0
	global_load_lds_dwordx4 v253, vcc
	s_add_i32 m0, s22, 0x2000
	s_nop 0
	global_load_lds_dwordx4 v254, vcc
	s_mov_b32 m0, s31
	s_add_u32 s34, s34, 0x100
	global_load_lds_dwordx4 v134, s[26:27]
	s_mov_b32 m0, s14
	s_addc_u32 s35, s35, 0
	global_load_lds_dwordx4 v138, s[26:27]
	s_waitcnt vmcnt(8)
	s_waitcnt lgkmcnt(0)
	s_barrier
	v_mfma_f32_16x16x32_bf16 v[62:65], v[130:133], v[182:185], 0
	v_mfma_f32_16x16x32_bf16 v[58:61], v[150:153], v[182:185], 0
	v_mfma_f32_16x16x32_bf16 v[46:49], v[130:133], v[190:193], 0
	v_mfma_f32_16x16x32_bf16 v[42:45], v[150:153], v[190:193], 0
	v_mfma_f32_16x16x32_bf16 v[30:33], v[130:133], v[220:223], 0
	v_mfma_f32_16x16x32_bf16 v[26:29], v[150:153], v[220:223], 0
	v_mfma_f32_16x16x32_bf16 v[14:17], v[130:133], v[228:231], 0
	v_mfma_f32_16x16x32_bf16 v[10:13], v[150:153], v[228:231], 0
	v_mfma_f32_16x16x32_bf16 v[62:65], v[146:149], v[186:189], v[62:65]
	v_mfma_f32_16x16x32_bf16 v[58:61], v[154:157], v[186:189], v[58:61]
	v_mfma_f32_16x16x32_bf16 v[46:49], v[146:149], v[216:219], v[46:49]
	v_mfma_f32_16x16x32_bf16 v[42:45], v[154:157], v[216:219], v[42:45]
	v_mfma_f32_16x16x32_bf16 v[30:33], v[146:149], v[224:227], v[30:33]
	v_mfma_f32_16x16x32_bf16 v[26:29], v[154:157], v[224:227], v[26:29]
	v_mfma_f32_16x16x32_bf16 v[14:17], v[146:149], v[236:239], v[14:17]
	v_mfma_f32_16x16x32_bf16 v[10:13], v[154:157], v[236:239], v[10:13]
	v_mfma_f32_16x16x32_bf16 v[54:57], v[162:165], v[182:185], 0
	v_mfma_f32_16x16x32_bf16 v[50:53], v[170:173], v[182:185], 0
	v_mfma_f32_16x16x32_bf16 v[38:41], v[162:165], v[190:193], 0
	v_mfma_f32_16x16x32_bf16 v[34:37], v[170:173], v[190:193], 0
	v_mfma_f32_16x16x32_bf16 v[22:25], v[162:165], v[220:223], 0
	v_mfma_f32_16x16x32_bf16 v[18:21], v[170:173], v[220:223], 0
	v_mfma_f32_16x16x32_bf16 v[6:9], v[162:165], v[228:231], 0
	v_mfma_f32_16x16x32_bf16 v[2:5], v[170:173], v[228:231], 0
	v_mfma_f32_16x16x32_bf16 v[54:57], v[166:169], v[186:189], v[54:57]
	v_mfma_f32_16x16x32_bf16 v[50:53], v[174:177], v[186:189], v[50:53]
	v_mfma_f32_16x16x32_bf16 v[38:41], v[166:169], v[216:219], v[38:41]
	v_mfma_f32_16x16x32_bf16 v[34:37], v[174:177], v[216:219], v[34:37]
	v_mfma_f32_16x16x32_bf16 v[22:25], v[166:169], v[224:227], v[22:25]
	v_mfma_f32_16x16x32_bf16 v[18:21], v[174:177], v[224:227], v[18:21]
	v_mfma_f32_16x16x32_bf16 v[6:9], v[166:169], v[236:239], v[6:9]
	v_mfma_f32_16x16x32_bf16 v[2:5], v[174:177], v[236:239], v[2:5]
	s_barrier
; #define PG8_STAGE(bufoff, gbase, voff) do { _Pragma("unroll") for (int _i = 0; _i < 2; ++_i) \
;         __builtin_amdgcn_global_load_lds((const unsigned*)((const char*)(gbase) + (voff)[_i]), (LAS unsigned*)(lds + (bufoff) + ldsw + _i * 8192), 16, 0, 0); } while (0)
; #define PG8_LDA(dst, b, h) do { _Pragma("unroll") for (int m = 0; m < 4; ++m) _Pragma("unroll") for (int k = 0; k < 2; ++k) dst[m][k] = *(const LAS bf16x8*)(lds + PG8_SA(b, h) + aoff + m * 2048 + k * 1024); } while (0)
; #define PG8_LDB(dst, b, h) do { _Pragma("unroll") for (int n = 0; n < 2; ++n) _Pragma("unroll") for (int k = 0; k < 2; ++k) dst[n][k] = *(const LAS bf16x8*)(lds + PG8_SB(b, h) + boff + n * 2048 + k * 1024); } while (0)
; #define PG8_MMA(ai, bj, At, Bt) do { __builtin_amdgcn_s_setprio(1); _Pragma("unroll") for (int m = 0; m < 4; ++m) _Pragma("unroll") for (int n = 0; n < 2; ++n) _Pragma("unroll") for (int k = 0; k < 2; ++k) \
;         acc[ai][bj][m][n] = __builtin_amdgcn_mfma_f32_16x16x32_bf16(Bt[n][k], At[m][k], acc[ai][bj][m][n], 0, 0, 0); __builtin_amdgcn_s_setprio(0); } while (0)
; #define PG8_WAIT_V(n) asm volatile("s_waitcnt vmcnt(" #n ")" ::: "memory")
; #define PG8_WAIT_L(n) asm volatile("s_waitcnt lgkmcnt(" #n ")" ::: "memory")
; #define PG8_BAR __builtin_amdgcn_s_barrier()
; #define PG8_SCHED __builtin_amdgcn_sched_barrier(0)
; __device__ __forceinline__ void gemm_phase(LAS unsigned char* lds, const GemmD g, const Sched& S, const Epi& E) {
;     ...
;             PG8_LDB(B0, 1, 0); PG8_LDB(B1, 1, 1); PG8_SCHED; PG8_LDA(At, 1, 0); PG8_STAGE(PG8_SA(0, 1), a2 + hstepA, voffA);
;             PG8_WAIT_V(8); PG8_WAIT_L(0); PG8_BAR; PG8_MMA(0, 0, At, B0); PG8_MMA(0, 1, At, B1); PG8_BAR; PG8_SCHED;
;             PG8_LDA(At, 1, 1); PG8_STAGE(PG8_SB(1, 0), b3, voffB); PG8_STAGE(PG8_SB(1, 1), b3 + hstepB, voffB); PG8_STAGE(PG8_SA(1, 0), a3, voffA);
;             PG8_WAIT_V(8); PG8_WAIT_L(0); PG8_BAR; PG8_MMA(1, 0, At, B0); PG8_MMA(1, 1, At, B1); PG8_BAR; PG8_SCHED;
;         }
	s_add_i32 s22, 0, 0x18000
	s_add_i32 s23, 0, 0x1c000
	ds_read_b128 v[130:133], v242
	ds_read_b128 v[146:149], v242 offset:1024
	ds_read_b128 v[150:153], v242 offset:2048
	ds_read_b128 v[154:157], v242 offset:3072
	ds_read_b128 v[162:165], v243
	ds_read_b128 v[166:169], v243 offset:1024
	ds_read_b128 v[170:173], v243 offset:2048
	ds_read_b128 v[174:177], v243 offset:3072
	s_mov_b32 m0, s15
	ds_read_b128 v[182:185], v161 offset:32768
	ds_read_b128 v[186:189], v161 offset:33792
	ds_read_b128 v[190:193], v161 offset:34816
	ds_read_b128 v[216:219], v161 offset:35840
	ds_read_b128 v[220:223], v161 offset:36864
	ds_read_b128 v[224:227], v161 offset:37888
	ds_read_b128 v[228:231], v161 offset:38912
	ds_read_b128 v[236:239], v161 offset:39936
	global_load_lds_dwordx4 v142, s[26:27]
	s_mov_b32 m0, s10
	s_nop 0
	global_load_lds_dwordx4 v144, s[26:27]
	s_waitcnt vmcnt(8)
	s_waitcnt lgkmcnt(0)
	s_barrier
	v_mfma_f32_16x16x32_bf16 v[126:129], v[130:133], v[182:185], v[126:129]
	v_mfma_f32_16x16x32_bf16 v[122:125], v[150:153], v[182:185], v[122:125]
	v_mfma_f32_16x16x32_bf16 v[110:113], v[130:133], v[190:193], v[110:113]
	v_mfma_f32_16x16x32_bf16 v[106:109], v[150:153], v[190:193], v[106:109]
	v_mfma_f32_16x16x32_bf16 v[94:97], v[130:133], v[220:223], v[94:97]
	v_mfma_f32_16x16x32_bf16 v[90:93], v[150:153], v[220:223], v[90:93]
	v_mfma_f32_16x16x32_bf16 v[78:81], v[130:133], v[228:231], v[78:81]
	v_mfma_f32_16x16x32_bf16 v[74:77], v[150:153], v[228:231], v[74:77]
	v_mfma_f32_16x16x32_bf16 v[126:129], v[146:149], v[186:189], v[126:129]
	v_mfma_f32_16x16x32_bf16 v[122:125], v[154:157], v[186:189], v[122:125]
	v_mfma_f32_16x16x32_bf16 v[110:113], v[146:149], v[216:219], v[110:113]
	v_mfma_f32_16x16x32_bf16 v[106:109], v[154:157], v[216:219], v[106:109]
	v_mfma_f32_16x16x32_bf16 v[94:97], v[146:149], v[224:227], v[94:97]
	v_mfma_f32_16x16x32_bf16 v[90:93], v[154:157], v[224:227], v[90:93]
	v_mfma_f32_16x16x32_bf16 v[78:81], v[146:149], v[236:239], v[78:81]
	v_mfma_f32_16x16x32_bf16 v[74:77], v[154:157], v[236:239], v[74:77]
	v_mfma_f32_16x16x32_bf16 v[118:121], v[162:165], v[182:185], v[118:121]
	v_mfma_f32_16x16x32_bf16 v[114:117], v[170:173], v[182:185], v[114:117]
	v_mfma_f32_16x16x32_bf16 v[102:105], v[162:165], v[190:193], v[102:105]
	v_mfma_f32_16x16x32_bf16 v[98:101], v[170:173], v[190:193], v[98:101]
	v_mfma_f32_16x16x32_bf16 v[86:89], v[162:165], v[220:223], v[86:89]
	v_mfma_f32_16x16x32_bf16 v[82:85], v[170:173], v[220:223], v[82:85]
	v_mfma_f32_16x16x32_bf16 v[70:73], v[162:165], v[228:231], v[70:73]
	v_mfma_f32_16x16x32_bf16 v[66:69], v[170:173], v[228:231], v[66:69]
	v_mfma_f32_16x16x32_bf16 v[118:121], v[166:169], v[186:189], v[118:121]
	v_mfma_f32_16x16x32_bf16 v[114:117], v[174:177], v[186:189], v[114:117]
	v_mfma_f32_16x16x32_bf16 v[102:105], v[166:169], v[216:219], v[102:105]
	v_mfma_f32_16x16x32_bf16 v[98:101], v[174:177], v[216:219], v[98:101]
	v_mfma_f32_16x16x32_bf16 v[86:89], v[166:169], v[224:227], v[86:89]
	v_mfma_f32_16x16x32_bf16 v[82:85], v[174:177], v[224:227], v[82:85]
	v_mfma_f32_16x16x32_bf16 v[70:73], v[166:169], v[236:239], v[70:73]
	v_mfma_f32_16x16x32_bf16 v[66:69], v[174:177], v[236:239], v[66:69]
	s_barrier
	ds_read_b128 v[182:185], v161 offset:49152
	ds_read_b128 v[186:189], v161 offset:50176
	ds_read_b128 v[190:193], v161 offset:51200
	ds_read_b128 v[216:219], v161 offset:52224
	ds_read_b128 v[220:223], v161 offset:53248
	ds_read_b128 v[224:227], v161 offset:54272
	ds_read_b128 v[228:231], v161 offset:55296
	s_add_i32 s22, s22, s30
	s_add_u32 vcc_lo, vcc_lo, s84
	s_addc_u32 vcc_hi, vcc_hi, s85
	s_add_u32 s26, s26, s84
	s_addc_u32 s27, s27, s85
	s_mov_b32 m0, s22
	ds_read_b128 v[236:239], v161 offset:56320
	global_load_lds_dwordx4 v136, vcc
	s_add_i32 m0, s22, 0x2000
	s_add_i32 s22, s23, s30
	global_load_lds_dwordx4 v140, vcc
	s_mov_b32 m0, s22
	s_nop 0
	global_load_lds_dwordx4 v253, vcc
	s_add_i32 m0, s22, 0x2000
	s_nop 0
	global_load_lds_dwordx4 v254, vcc
	s_mov_b32 m0, s18
	s_add_u32 s8, s8, 0x100
	global_load_lds_dwordx4 v134, s[26:27]
	s_mov_b32 m0, s19
	s_addc_u32 s9, s9, 0
	global_load_lds_dwordx4 v138, s[26:27]
	s_mov_b32 s26, s92
	s_cmp_ge_u32 s92, s12
	s_waitcnt vmcnt(8)
	s_waitcnt lgkmcnt(0)
	s_barrier
	v_mfma_f32_16x16x32_bf16 v[62:65], v[130:133], v[182:185], v[62:65]
	v_mfma_f32_16x16x32_bf16 v[58:61], v[150:153], v[182:185], v[58:61]
	v_mfma_f32_16x16x32_bf16 v[46:49], v[130:133], v[190:193], v[46:49]
	v_mfma_f32_16x16x32_bf16 v[42:45], v[150:153], v[190:193], v[42:45]
	v_mfma_f32_16x16x32_bf16 v[30:33], v[130:133], v[220:223], v[30:33]
	v_mfma_f32_16x16x32_bf16 v[26:29], v[150:153], v[220:223], v[26:29]
	v_mfma_f32_16x16x32_bf16 v[14:17], v[130:133], v[228:231], v[14:17]
	v_mfma_f32_16x16x32_bf16 v[10:13], v[150:153], v[228:231], v[10:13]
	v_mfma_f32_16x16x32_bf16 v[62:65], v[146:149], v[186:189], v[62:65]
	v_mfma_f32_16x16x32_bf16 v[58:61], v[154:157], v[186:189], v[58:61]
	v_mfma_f32_16x16x32_bf16 v[46:49], v[146:149], v[216:219], v[46:49]
	v_mfma_f32_16x16x32_bf16 v[42:45], v[154:157], v[216:219], v[42:45]
	v_mfma_f32_16x16x32_bf16 v[30:33], v[146:149], v[224:227], v[30:33]
	v_mfma_f32_16x16x32_bf16 v[26:29], v[154:157], v[224:227], v[26:29]
	v_mfma_f32_16x16x32_bf16 v[14:17], v[146:149], v[236:239], v[14:17]
	v_mfma_f32_16x16x32_bf16 v[10:13], v[154:157], v[236:239], v[10:13]
	v_mfma_f32_16x16x32_bf16 v[54:57], v[162:165], v[182:185], v[54:57]
	v_mfma_f32_16x16x32_bf16 v[50:53], v[170:173], v[182:185], v[50:53]
	v_mfma_f32_16x16x32_bf16 v[38:41], v[162:165], v[190:193], v[38:41]
	v_mfma_f32_16x16x32_bf16 v[34:37], v[170:173], v[190:193], v[34:37]
	v_mfma_f32_16x16x32_bf16 v[22:25], v[162:165], v[220:223], v[22:25]
	v_mfma_f32_16x16x32_bf16 v[18:21], v[170:173], v[220:223], v[18:21]
	v_mfma_f32_16x16x32_bf16 v[6:9], v[162:165], v[228:231], v[6:9]
	v_mfma_f32_16x16x32_bf16 v[2:5], v[170:173], v[228:231], v[2:5]
	v_mfma_f32_16x16x32_bf16 v[54:57], v[166:169], v[186:189], v[54:57]
	v_mfma_f32_16x16x32_bf16 v[50:53], v[174:177], v[186:189], v[50:53]
	v_mfma_f32_16x16x32_bf16 v[38:41], v[166:169], v[216:219], v[38:41]
	v_mfma_f32_16x16x32_bf16 v[34:37], v[174:177], v[216:219], v[34:37]
	v_mfma_f32_16x16x32_bf16 v[22:25], v[166:169], v[224:227], v[22:25]
	v_mfma_f32_16x16x32_bf16 v[18:21], v[174:177], v[224:227], v[18:21]
	v_mfma_f32_16x16x32_bf16 v[6:9], v[166:169], v[236:239], v[6:9]
	v_mfma_f32_16x16x32_bf16 v[2:5], v[174:177], v[236:239], v[2:5]
	s_barrier
	s_cbranch_scc0 .LBB0_215
	s_branch .Lgemm_after
; #define PG8_STAGE(bufoff, gbase, voff) do { _Pragma("unroll") for (int _i = 0; _i < 2; ++_i) \
;         __builtin_amdgcn_global_load_lds((const unsigned*)((const char*)(gbase) + (voff)[_i]), (LAS unsigned*)(lds + (bufoff) + ldsw + _i * 8192), 16, 0, 0); } while (0)
; #define PG8_LDA(dst, b, h) do { _Pragma("unroll") for (int m = 0; m < 4; ++m) _Pragma("unroll") for (int k = 0; k < 2; ++k) dst[m][k] = *(const LAS bf16x8*)(lds + PG8_SA(b, h) + aoff + m * 2048 + k * 1024); } while (0)
; #define PG8_LDB(dst, b, h) do { _Pragma("unroll") for (int n = 0; n < 2; ++n) _Pragma("unroll") for (int k = 0; k < 2; ++k) dst[n][k] = *(const LAS bf16x8*)(lds + PG8_SB(b, h) + boff + n * 2048 + k * 1024); } while (0)
; #define PG8_MMA(ai, bj, At, Bt) do { __builtin_amdgcn_s_setprio(1); _Pragma("unroll") for (int m = 0; m < 4; ++m) _Pragma("unroll") for (int n = 0; n < 2; ++n) _Pragma("unroll") for (int k = 0; k < 2; ++k) \
;         acc[ai][bj][m][n] = __builtin_amdgcn_mfma_f32_16x16x32_bf16(Bt[n][k], At[m][k], acc[ai][bj][m][n], 0, 0, 0); __builtin_amdgcn_s_setprio(0); } while (0)
; #define PG8_WAIT_V(n) asm volatile("s_waitcnt vmcnt(" #n ")" ::: "memory")
; #define PG8_WAIT_L(n) asm volatile("s_waitcnt lgkmcnt(" #n ")" ::: "memory")
; #define PG8_BAR __builtin_amdgcn_s_barrier()
; #define PG8_SCHED __builtin_amdgcn_sched_barrier(0)
; __device__ __forceinline__ void gemm_phase(LAS unsigned char* lds, const GemmD g, const Sched& S, const Epi& E) {
;     ...
;             const bool last = (t == nt - 2);
;             const char* a1 = cA + (size_t)(t + 1) * kstep;
;             const char* a2 = last ? nA : cA + (size_t)(t + 2) * kstep; const char* b2 = last ? nB : cB + (size_t)(t + 2) * kstep;
;             const char* a3 = a2 + kstep; const char* b3 = b2 + kstep;
;             PG8_LDB(B0, 0, 0); PG8_LDB(B1, 0, 1); PG8_SCHED; PG8_LDA(At, 0, 0); PG8_STAGE(PG8_SA(1, 1), a1 + hstepA, voffA);
;             PG8_WAIT_V(8); PG8_WAIT_L(0); PG8_BAR; PG8_MMA(0, 0, At, B0); PG8_MMA(0, 1, At, B1); PG8_BAR; PG8_SCHED;
;             PG8_LDA(At, 0, 1); PG8_STAGE(PG8_SB(0, 0), b2, voffB); PG8_STAGE(PG8_SB(0, 1), b2 + hstepB, voffB); PG8_STAGE(PG8_SA(0, 0), a2, voffA);
;             PG8_WAIT_V(8); PG8_WAIT_L(0); PG8_BAR; PG8_MMA(1, 0, At, B0); PG8_MMA(1, 1, At, B1); PG8_BAR; PG8_SCHED;
.LBB0_215:
	ds_read_b128 v[130:133], v240
	ds_read_b128 v[146:149], v240 offset:1024
	ds_read_b128 v[150:153], v240 offset:2048
	ds_read_b128 v[154:157], v240 offset:3072
	ds_read_b128 v[162:165], v241
	ds_read_b128 v[166:169], v241 offset:1024
	ds_read_b128 v[170:173], v241 offset:2048
	ds_read_b128 v[174:177], v241 offset:3072
	s_add_i32 m0, s31, 0xc000
	ds_read_b128 v[182:185], v161
	ds_read_b128 v[186:189], v161 offset:1024
	ds_read_b128 v[190:193], v161 offset:2048
	ds_read_b128 v[216:219], v161 offset:3072
	ds_read_b128 v[220:223], v161 offset:4096
	ds_read_b128 v[224:227], v161 offset:5120
	ds_read_b128 v[228:231], v161 offset:6144
	ds_read_b128 v[236:239], v161 offset:7168
	global_load_lds_dwordx4 v142, s[8:9]
	s_add_i32 m0, s31, 0xe000
	s_nop 0
	global_load_lds_dwordx4 v144, s[8:9]
	s_add_i32 s92, s26, 2
	s_add_u32 s93, s8, 0x80
	s_addc_u32 s27, s9, 0
	s_add_i32 s22, 0, 0x10000
	s_cmp_eq_u32 s11, s26
	s_cselect_b32 s27, s1, s27
	s_cselect_b32 s26, s0, s93
	s_cselect_b32 vcc_hi, s17, s35
	s_cselect_b32 vcc_lo, s16, s34
	s_add_i32 s23, 0, 0x14000
	s_waitcnt vmcnt(8)
	s_waitcnt lgkmcnt(0)
	s_barrier
	v_mfma_f32_16x16x32_bf16 v[126:129], v[130:133], v[182:185], v[126:129]
	v_mfma_f32_16x16x32_bf16 v[122:125], v[150:153], v[182:185], v[122:125]
	v_mfma_f32_16x16x32_bf16 v[110:113], v[130:133], v[190:193], v[110:113]
	v_mfma_f32_16x16x32_bf16 v[106:109], v[150:153], v[190:193], v[106:109]
	v_mfma_f32_16x16x32_bf16 v[94:97], v[130:133], v[220:223], v[94:97]
	v_mfma_f32_16x16x32_bf16 v[90:93], v[150:153], v[220:223], v[90:93]
	v_mfma_f32_16x16x32_bf16 v[78:81], v[130:133], v[228:231], v[78:81]
	v_mfma_f32_16x16x32_bf16 v[74:77], v[150:153], v[228:231], v[74:77]
	v_mfma_f32_16x16x32_bf16 v[126:129], v[146:149], v[186:189], v[126:129]
	v_mfma_f32_16x16x32_bf16 v[122:125], v[154:157], v[186:189], v[122:125]
	v_mfma_f32_16x16x32_bf16 v[110:113], v[146:149], v[216:219], v[110:113]
	v_mfma_f32_16x16x32_bf16 v[106:109], v[154:157], v[216:219], v[106:109]
	v_mfma_f32_16x16x32_bf16 v[94:97], v[146:149], v[224:227], v[94:97]
	v_mfma_f32_16x16x32_bf16 v[90:93], v[154:157], v[224:227], v[90:93]
	v_mfma_f32_16x16x32_bf16 v[78:81], v[146:149], v[236:239], v[78:81]
	v_mfma_f32_16x16x32_bf16 v[74:77], v[154:157], v[236:239], v[74:77]
	v_mfma_f32_16x16x32_bf16 v[118:121], v[162:165], v[182:185], v[118:121]
	v_mfma_f32_16x16x32_bf16 v[114:117], v[170:173], v[182:185], v[114:117]
	v_mfma_f32_16x16x32_bf16 v[102:105], v[162:165], v[190:193], v[102:105]
	v_mfma_f32_16x16x32_bf16 v[98:101], v[170:173], v[190:193], v[98:101]
	v_mfma_f32_16x16x32_bf16 v[86:89], v[162:165], v[220:223], v[86:89]
	v_mfma_f32_16x16x32_bf16 v[82:85], v[170:173], v[220:223], v[82:85]
	v_mfma_f32_16x16x32_bf16 v[70:73], v[162:165], v[228:231], v[70:73]
	v_mfma_f32_16x16x32_bf16 v[66:69], v[170:173], v[228:231], v[66:69]
	v_mfma_f32_16x16x32_bf16 v[118:121], v[166:169], v[186:189], v[118:121]
	v_mfma_f32_16x16x32_bf16 v[114:117], v[174:177], v[186:189], v[114:117]
	v_mfma_f32_16x16x32_bf16 v[102:105], v[166:169], v[216:219], v[102:105]
	v_mfma_f32_16x16x32_bf16 v[98:101], v[174:177], v[216:219], v[98:101]
	v_mfma_f32_16x16x32_bf16 v[86:89], v[166:169], v[224:227], v[86:89]
	v_mfma_f32_16x16x32_bf16 v[82:85], v[174:177], v[224:227], v[82:85]
	v_mfma_f32_16x16x32_bf16 v[70:73], v[166:169], v[236:239], v[70:73]
	v_mfma_f32_16x16x32_bf16 v[66:69], v[174:177], v[236:239], v[66:69]
	s_barrier
	ds_read_b128 v[182:185], v161 offset:16384
	ds_read_b128 v[186:189], v161 offset:17408
	ds_read_b128 v[190:193], v161 offset:18432
	ds_read_b128 v[216:219], v161 offset:19456
	ds_read_b128 v[220:223], v161 offset:20480
	ds_read_b128 v[224:227], v161 offset:21504
	ds_read_b128 v[228:231], v161 offset:22528
	s_add_i32 s22, s22, s30
	s_mov_b32 m0, s22
	ds_read_b128 v[236:239], v161 offset:23552
	global_load_lds_dwordx4 v136, vcc
	s_add_i32 m0, s22, 0x2000
	s_add_i32 s22, s23, s30
	global_load_lds_dwordx4 v140, vcc
	s_mov_b32 m0, s22
	s_nop 0
	global_load_lds_dwordx4 v253, vcc
	s_add_i32 m0, s22, 0x2000
	s_nop 0
	global_load_lds_dwordx4 v254, vcc
	s_mov_b32 m0, s31
	s_add_u32 s34, s34, 0x100
	global_load_lds_dwordx4 v134, s[26:27]
	s_mov_b32 m0, s14
	s_addc_u32 s35, s35, 0
	global_load_lds_dwordx4 v138, s[26:27]
	s_waitcnt vmcnt(8)
	s_waitcnt lgkmcnt(0)
	s_barrier
	v_mfma_f32_16x16x32_bf16 v[62:65], v[130:133], v[182:185], v[62:65]
	v_mfma_f32_16x16x32_bf16 v[58:61], v[150:153], v[182:185], v[58:61]
	v_mfma_f32_16x16x32_bf16 v[46:49], v[130:133], v[190:193], v[46:49]
	v_mfma_f32_16x16x32_bf16 v[42:45], v[150:153], v[190:193], v[42:45]
	v_mfma_f32_16x16x32_bf16 v[30:33], v[130:133], v[220:223], v[30:33]
	v_mfma_f32_16x16x32_bf16 v[26:29], v[150:153], v[220:223], v[26:29]
	v_mfma_f32_16x16x32_bf16 v[14:17], v[130:133], v[228:231], v[14:17]
	v_mfma_f32_16x16x32_bf16 v[10:13], v[150:153], v[228:231], v[10:13]
	v_mfma_f32_16x16x32_bf16 v[62:65], v[146:149], v[186:189], v[62:65]
	v_mfma_f32_16x16x32_bf16 v[58:61], v[154:157], v[186:189], v[58:61]
	v_mfma_f32_16x16x32_bf16 v[46:49], v[146:149], v[216:219], v[46:49]
	v_mfma_f32_16x16x32_bf16 v[42:45], v[154:157], v[216:219], v[42:45]
	v_mfma_f32_16x16x32_bf16 v[30:33], v[146:149], v[224:227], v[30:33]
	v_mfma_f32_16x16x32_bf16 v[26:29], v[154:157], v[224:227], v[26:29]
	v_mfma_f32_16x16x32_bf16 v[14:17], v[146:149], v[236:239], v[14:17]
	v_mfma_f32_16x16x32_bf16 v[10:13], v[154:157], v[236:239], v[10:13]
	v_mfma_f32_16x16x32_bf16 v[54:57], v[162:165], v[182:185], v[54:57]
	v_mfma_f32_16x16x32_bf16 v[50:53], v[170:173], v[182:185], v[50:53]
	v_mfma_f32_16x16x32_bf16 v[38:41], v[162:165], v[190:193], v[38:41]
	v_mfma_f32_16x16x32_bf16 v[34:37], v[170:173], v[190:193], v[34:37]
	v_mfma_f32_16x16x32_bf16 v[22:25], v[162:165], v[220:223], v[22:25]
	v_mfma_f32_16x16x32_bf16 v[18:21], v[170:173], v[220:223], v[18:21]
	v_mfma_f32_16x16x32_bf16 v[6:9], v[162:165], v[228:231], v[6:9]
	v_mfma_f32_16x16x32_bf16 v[2:5], v[170:173], v[228:231], v[2:5]
	v_mfma_f32_16x16x32_bf16 v[54:57], v[166:169], v[186:189], v[54:57]
	v_mfma_f32_16x16x32_bf16 v[50:53], v[174:177], v[186:189], v[50:53]
	v_mfma_f32_16x16x32_bf16 v[38:41], v[166:169], v[216:219], v[38:41]
	v_mfma_f32_16x16x32_bf16 v[34:37], v[174:177], v[216:219], v[34:37]
	v_mfma_f32_16x16x32_bf16 v[22:25], v[166:169], v[224:227], v[22:25]
	v_mfma_f32_16x16x32_bf16 v[18:21], v[174:177], v[224:227], v[18:21]
	v_mfma_f32_16x16x32_bf16 v[6:9], v[166:169], v[236:239], v[6:9]
	v_mfma_f32_16x16x32_bf16 v[2:5], v[174:177], v[236:239], v[2:5]
	s_barrier
; #define PG8_STAGE(bufoff, gbase, voff) do { _Pragma("unroll") for (int _i = 0; _i < 2; ++_i) \
;         __builtin_amdgcn_global_load_lds((const unsigned*)((const char*)(gbase) + (voff)[_i]), (LAS unsigned*)(lds + (bufoff) + ldsw + _i * 8192), 16, 0, 0); } while (0)
; #define PG8_LDA(dst, b, h) do { _Pragma("unroll") for (int m = 0; m < 4; ++m) _Pragma("unroll") for (int k = 0; k < 2; ++k) dst[m][k] = *(const LAS bf16x8*)(lds + PG8_SA(b, h) + aoff + m * 2048 + k * 1024); } while (0)
; #define PG8_LDB(dst, b, h) do { _Pragma("unroll") for (int n = 0; n < 2; ++n) _Pragma("unroll") for (int k = 0; k < 2; ++k) dst[n][k] = *(const LAS bf16x8*)(lds + PG8_SB(b, h) + boff + n * 2048 + k * 1024); } while (0)
; #define PG8_MMA(ai, bj, At, Bt) do { __builtin_amdgcn_s_setprio(1); _Pragma("unroll") for (int m = 0; m < 4; ++m) _Pragma("unroll") for (int n = 0; n < 2; ++n) _Pragma("unroll") for (int k = 0; k < 2; ++k) \
;         acc[ai][bj][m][n] = __builtin_amdgcn_mfma_f32_16x16x32_bf16(Bt[n][k], At[m][k], acc[ai][bj][m][n], 0, 0, 0); __builtin_amdgcn_s_setprio(0); } while (0)
; #define PG8_WAIT_V(n) asm volatile("s_waitcnt vmcnt(" #n ")" ::: "memory")
; #define PG8_WAIT_L(n) asm volatile("s_waitcnt lgkmcnt(" #n ")" ::: "memory")
; #define PG8_BAR __builtin_amdgcn_s_barrier()
; #define PG8_SCHED __builtin_amdgcn_sched_barrier(0)
; __device__ __forceinline__ void gemm_phase(LAS unsigned char* lds, const GemmD g, const Sched& S, const Epi& E) {
;     ...
;             PG8_LDB(B0, 1, 0); PG8_LDB(B1, 1, 1); PG8_SCHED; PG8_LDA(At, 1, 0); PG8_STAGE(PG8_SA(0, 1), a2 + hstepA, voffA);
;             PG8_WAIT_V(8); PG8_WAIT_L(0); PG8_BAR; PG8_MMA(0, 0, At, B0); PG8_MMA(0, 1, At, B1); PG8_BAR; PG8_SCHED;
;             PG8_LDA(At, 1, 1); PG8_STAGE(PG8_SB(1, 0), b3, voffB); PG8_STAGE(PG8_SB(1, 1), b3 + hstepB, voffB); PG8_STAGE(PG8_SA(1, 0), a3, voffA);
;             PG8_WAIT_V(8); PG8_WAIT_L(0); PG8_BAR; PG8_MMA(1, 0, At, B0); PG8_MMA(1, 1, At, B1); PG8_BAR; PG8_SCHED;
;         }
	s_add_i32 s22, 0, 0x18000
	s_add_i32 s23, 0, 0x1c000
	ds_read_b128 v[130:133], v242
	ds_read_b128 v[146:149], v242 offset:1024
	ds_read_b128 v[150:153], v242 offset:2048
	ds_read_b128 v[154:157], v242 offset:3072
	ds_read_b128 v[162:165], v243
	ds_read_b128 v[166:169], v243 offset:1024
	ds_read_b128 v[170:173], v243 offset:2048
	ds_read_b128 v[174:177], v243 offset:3072
	s_mov_b32 m0, s15
	ds_read_b128 v[182:185], v161 offset:32768
	ds_read_b128 v[186:189], v161 offset:33792
	ds_read_b128 v[190:193], v161 offset:34816
	ds_read_b128 v[216:219], v161 offset:35840
	ds_read_b128 v[220:223], v161 offset:36864
	ds_read_b128 v[224:227], v161 offset:37888
	ds_read_b128 v[228:231], v161 offset:38912
	ds_read_b128 v[236:239], v161 offset:39936
	global_load_lds_dwordx4 v142, s[26:27]
	s_mov_b32 m0, s10
	s_nop 0
	global_load_lds_dwordx4 v144, s[26:27]
	s_waitcnt vmcnt(8)
	s_waitcnt lgkmcnt(0)
	s_barrier
	v_mfma_f32_16x16x32_bf16 v[126:129], v[130:133], v[182:185], v[126:129]
	v_mfma_f32_16x16x32_bf16 v[122:125], v[150:153], v[182:185], v[122:125]
	v_mfma_f32_16x16x32_bf16 v[110:113], v[130:133], v[190:193], v[110:113]
	v_mfma_f32_16x16x32_bf16 v[106:109], v[150:153], v[190:193], v[106:109]
	v_mfma_f32_16x16x32_bf16 v[94:97], v[130:133], v[220:223], v[94:97]
	v_mfma_f32_16x16x32_bf16 v[90:93], v[150:153], v[220:223], v[90:93]
	v_mfma_f32_16x16x32_bf16 v[78:81], v[130:133], v[228:231], v[78:81]
	v_mfma_f32_16x16x32_bf16 v[74:77], v[150:153], v[228:231], v[74:77]
	v_mfma_f32_16x16x32_bf16 v[126:129], v[146:149], v[186:189], v[126:129]
	v_mfma_f32_16x16x32_bf16 v[122:125], v[154:157], v[186:189], v[122:125]
	v_mfma_f32_16x16x32_bf16 v[110:113], v[146:149], v[216:219], v[110:113]
	v_mfma_f32_16x16x32_bf16 v[106:109], v[154:157], v[216:219], v[106:109]
	v_mfma_f32_16x16x32_bf16 v[94:97], v[146:149], v[224:227], v[94:97]
	v_mfma_f32_16x16x32_bf16 v[90:93], v[154:157], v[224:227], v[90:93]
	v_mfma_f32_16x16x32_bf16 v[78:81], v[146:149], v[236:239], v[78:81]
	v_mfma_f32_16x16x32_bf16 v[74:77], v[154:157], v[236:239], v[74:77]
	v_mfma_f32_16x16x32_bf16 v[118:121], v[162:165], v[182:185], v[118:121]
	v_mfma_f32_16x16x32_bf16 v[114:117], v[170:173], v[182:185], v[114:117]
	v_mfma_f32_16x16x32_bf16 v[102:105], v[162:165], v[190:193], v[102:105]
	v_mfma_f32_16x16x32_bf16 v[98:101], v[170:173], v[190:193], v[98:101]
	v_mfma_f32_16x16x32_bf16 v[86:89], v[162:165], v[220:223], v[86:89]
	v_mfma_f32_16x16x32_bf16 v[82:85], v[170:173], v[220:223], v[82:85]
	v_mfma_f32_16x16x32_bf16 v[70:73], v[162:165], v[228:231], v[70:73]
	v_mfma_f32_16x16x32_bf16 v[66:69], v[170:173], v[228:231], v[66:69]
	v_mfma_f32_16x16x32_bf16 v[118:121], v[166:169], v[186:189], v[118:121]
	v_mfma_f32_16x16x32_bf16 v[114:117], v[174:177], v[186:189], v[114:117]
	v_mfma_f32_16x16x32_bf16 v[102:105], v[166:169], v[216:219], v[102:105]
	v_mfma_f32_16x16x32_bf16 v[98:101], v[174:177], v[216:219], v[98:101]
	v_mfma_f32_16x16x32_bf16 v[86:89], v[166:169], v[224:227], v[86:89]
	v_mfma_f32_16x16x32_bf16 v[82:85], v[174:177], v[224:227], v[82:85]
	v_mfma_f32_16x16x32_bf16 v[70:73], v[166:169], v[236:239], v[70:73]
	v_mfma_f32_16x16x32_bf16 v[66:69], v[174:177], v[236:239], v[66:69]
	s_barrier
	ds_read_b128 v[182:185], v161 offset:49152
	ds_read_b128 v[186:189], v161 offset:50176
	ds_read_b128 v[190:193], v161 offset:51200
	ds_read_b128 v[216:219], v161 offset:52224
	ds_read_b128 v[220:223], v161 offset:53248
	ds_read_b128 v[224:227], v161 offset:54272
	ds_read_b128 v[228:231], v161 offset:55296
	s_add_i32 s22, s22, s30
	s_add_u32 vcc_lo, vcc_lo, s84
	s_addc_u32 vcc_hi, vcc_hi, s85
	s_add_u32 s26, s26, s84
	s_addc_u32 s27, s27, s85
	s_mov_b32 m0, s22
	ds_read_b128 v[236:239], v161 offset:56320
	global_load_lds_dwordx4 v136, vcc
	s_add_i32 m0, s22, 0x2000
	s_add_i32 s22, s23, s30
	global_load_lds_dwordx4 v140, vcc
	s_mov_b32 m0, s22
	s_nop 0
	global_load_lds_dwordx4 v253, vcc
	s_add_i32 m0, s22, 0x2000
	s_nop 0
	global_load_lds_dwordx4 v254, vcc
	s_mov_b32 m0, s18
	s_add_u32 s8, s8, 0x100
	global_load_lds_dwordx4 v134, s[26:27]
	s_mov_b32 m0, s19
	s_addc_u32 s9, s9, 0
	global_load_lds_dwordx4 v138, s[26:27]
	s_mov_b32 s26, s92
	s_cmp_ge_u32 s92, s12
	s_waitcnt vmcnt(8)
	s_waitcnt lgkmcnt(0)
	s_barrier
	v_mfma_f32_16x16x32_bf16 v[62:65], v[130:133], v[182:185], v[62:65]
	v_mfma_f32_16x16x32_bf16 v[58:61], v[150:153], v[182:185], v[58:61]
	v_mfma_f32_16x16x32_bf16 v[46:49], v[130:133], v[190:193], v[46:49]
	v_mfma_f32_16x16x32_bf16 v[42:45], v[150:153], v[190:193], v[42:45]
	v_mfma_f32_16x16x32_bf16 v[30:33], v[130:133], v[220:223], v[30:33]
	v_mfma_f32_16x16x32_bf16 v[26:29], v[150:153], v[220:223], v[26:29]
	v_mfma_f32_16x16x32_bf16 v[14:17], v[130:133], v[228:231], v[14:17]
	v_mfma_f32_16x16x32_bf16 v[10:13], v[150:153], v[228:231], v[10:13]
	v_mfma_f32_16x16x32_bf16 v[62:65], v[146:149], v[186:189], v[62:65]
	v_mfma_f32_16x16x32_bf16 v[58:61], v[154:157], v[186:189], v[58:61]
	v_mfma_f32_16x16x32_bf16 v[46:49], v[146:149], v[216:219], v[46:49]
	v_mfma_f32_16x16x32_bf16 v[42:45], v[154:157], v[216:219], v[42:45]
	v_mfma_f32_16x16x32_bf16 v[30:33], v[146:149], v[224:227], v[30:33]
	v_mfma_f32_16x16x32_bf16 v[26:29], v[154:157], v[224:227], v[26:29]
	v_mfma_f32_16x16x32_bf16 v[14:17], v[146:149], v[236:239], v[14:17]
	v_mfma_f32_16x16x32_bf16 v[10:13], v[154:157], v[236:239], v[10:13]
	v_mfma_f32_16x16x32_bf16 v[54:57], v[162:165], v[182:185], v[54:57]
	v_mfma_f32_16x16x32_bf16 v[50:53], v[170:173], v[182:185], v[50:53]
	v_mfma_f32_16x16x32_bf16 v[38:41], v[162:165], v[190:193], v[38:41]
	v_mfma_f32_16x16x32_bf16 v[34:37], v[170:173], v[190:193], v[34:37]
	v_mfma_f32_16x16x32_bf16 v[22:25], v[162:165], v[220:223], v[22:25]
	v_mfma_f32_16x16x32_bf16 v[18:21], v[170:173], v[220:223], v[18:21]
	v_mfma_f32_16x16x32_bf16 v[6:9], v[162:165], v[228:231], v[6:9]
	v_mfma_f32_16x16x32_bf16 v[2:5], v[170:173], v[228:231], v[2:5]
	v_mfma_f32_16x16x32_bf16 v[54:57], v[166:169], v[186:189], v[54:57]
	v_mfma_f32_16x16x32_bf16 v[50:53], v[174:177], v[186:189], v[50:53]
	v_mfma_f32_16x16x32_bf16 v[38:41], v[166:169], v[216:219], v[38:41]
	v_mfma_f32_16x16x32_bf16 v[34:37], v[174:177], v[216:219], v[34:37]
	v_mfma_f32_16x16x32_bf16 v[22:25], v[166:169], v[224:227], v[22:25]
	v_mfma_f32_16x16x32_bf16 v[18:21], v[174:177], v[224:227], v[18:21]
	v_mfma_f32_16x16x32_bf16 v[6:9], v[166:169], v[236:239], v[6:9]
	v_mfma_f32_16x16x32_bf16 v[2:5], v[174:177], v[236:239], v[2:5]
	s_barrier
	s_cbranch_scc0 .LBB0_215
